# wave-priority: s_setprio 1/0 around A3 QK and PV MFMA clusters (on top of v21)
# baseline (speedup 1.0000x reference)
; #define LAS __attribute__((address_space(3)))
; #define MFMA32(a, b, c) __builtin_amdgcn_mfma_f32_32x32x16_bf16((a), (b), (c), 0, 0, 0)
;     ...
;         const int key0 = kt * KT + sub * 32 * NKB;
;         if ((MODE == 0 || key0 <= q0 + 31) && PV != 2) {
;             unsigned long long mw[NKB / 2];
;             if (MODE == 0) {
; #pragma unroll
;                 for (int w = 0; w < NKB / 2; ++w) mw[w] = MASK64[(rowbase + q0 + r) * 32 + (key0 >> 6) + w];
;             }
;             f32x16 sv[NKB];
; #pragma unroll
;             for (int kb2 = 0; kb2 < NKB; ++kb2)
; #pragma unroll
;                 for (int i = 0; i < 16; ++i) sv[kb2][i] = nm_run;
;             const LAS unsigned char* kb_ = lds + st * STAGE + koff + sub * 32 * NKB * KP;
; #pragma unroll
;             for (int kh = 0; kh < 2; ++kh) {
;                 bf16x8 kfr[2][NKB];
; #pragma unroll
;                 for (int k2 = 0; k2 < 2; ++k2)
; #pragma unroll
;                     for (int kb2 = 0; kb2 < NKB; ++kb2) kfr[k2][kb2] = *(const LAS bf16x8*)(kb_ + (32 * kb2 + r) * KP + (2 * kh + k2) * 32 + h * 16);
;                 if (NKB == 2) asm volatile("" : "+v"(kfr[0][0]), "+v"(kfr[0][1]), "+v"(kfr[1][0]), "+v"(kfr[1][1]));
;                 else asm volatile("" : "+v"(kfr[0][0]), "+v"(kfr[0][1]), "+v"(kfr[0][NKB - 2]), "+v"(kfr[0][NKB - 1]), "+v"(kfr[1][0]), "+v"(kfr[1][1]), "+v"(kfr[1][NKB - 2]), "+v"(kfr[1][NKB - 1]));
; #pragma unroll
;                 for (int k2 = 0; k2 < 2; ++k2)
; #pragma unroll
;                     for (int kb2 = 0; kb2 < NKB; ++kb2) sv[kb2] = MFMA32(kfr[k2][kb2], qf[2 * kh + k2], sv[kb2]);
;             }
;             if (MODE == 0) {
; #pragma unroll
;                 for (int kb2 = 0; kb2 < NKB; ++kb2) {
;                     const unsigned wsel = ((kb2 & 1) ? (unsigned)(mw[kb2 >> 1] >> 32) : (unsigned)mw[kb2 >> 1]) >> (4 * h);
; #pragma unroll
;                     for (int i = 0; i < 16; ++i) { const int cb = (i & 3) + 8 * (i >> 2); if (!((wsel >> cb) & 1u)) sv[kb2][i] = -1e30f; }
.LBB0_522:
	v_lshl_add_u64 v[34:35], s[0:1], 0, v[166:167]
	v_add_co_u32_e32 v34, vcc, 0x1d600000, v34
	s_and_b32 s7, s6, 1
	s_nop 0
	v_addc_co_u32_e32 v35, vcc, 0, v35, vcc
	global_load_dwordx4 v[132:135], v[34:35], off
	s_mul_i32 s9, s7, 0x8a00
	s_add_i32 s9, s9, 0
	v_add3_u32 v185, s9, v180, v182
	ds_read_b128 v[186:189], v185 offset:13856
	ds_read_b128 v[190:193], v185 offset:9248
	ds_read_b128 v[200:203], v185 offset:4640
	ds_read_b128 v[204:207], v185 offset:13824
	ds_read_b128 v[208:211], v185 offset:9216
	ds_read_b128 v[48:51], v185 offset:4608
	ds_read_b128 v[52:55], v185
	ds_read_b128 v[212:215], v185 offset:32
	v_mov_b32_e32 v33, v32
	v_mov_b32_e32 v34, v32
	v_mov_b32_e32 v35, v32
	v_mov_b32_e32 v36, v32
	v_mov_b32_e32 v37, v32
	v_mov_b32_e32 v38, v32
	v_mov_b32_e32 v39, v32
	v_mov_b32_e32 v40, v32
	v_mov_b32_e32 v41, v32
	v_mov_b32_e32 v42, v32
	v_mov_b32_e32 v43, v32
	v_mov_b32_e32 v44, v32
	v_mov_b32_e32 v45, v32
	v_mov_b32_e32 v46, v32
	v_mov_b32_e32 v47, v32
	s_waitcnt lgkmcnt(0)
	s_nop 0
	s_setprio 1
	v_mfma_f32_32x32x16_bf16 v[82:97], v[52:55], v[100:103], v[32:47]
	v_mfma_f32_32x32x16_bf16 v[66:81], v[48:51], v[100:103], v[32:47]
	v_mfma_f32_32x32x16_bf16 v[50:65], v[208:211], v[100:103], v[32:47]
	v_mov_b64_e32 v[48:49], v[46:47]
	s_nop 5
	v_mov_b64_e32 v[46:47], v[44:45]
	v_mov_b64_e32 v[44:45], v[42:43]
	v_mov_b64_e32 v[42:43], v[40:41]
	v_mov_b64_e32 v[40:41], v[38:39]
	v_mov_b64_e32 v[38:39], v[36:37]
	v_mov_b64_e32 v[36:37], v[34:35]
	v_mov_b64_e32 v[34:35], v[32:33]
	v_mfma_f32_32x32x16_bf16 v[82:97], v[212:215], v[104:107], v[82:97]
	s_waitcnt vmcnt(0)
	v_lshrrev_b32_e32 v132, v150, v132
	v_lshrrev_b32_e32 v133, v150, v133
	v_lshrrev_b32_e32 v134, v150, v134
	v_lshrrev_b32_e32 v135, v150, v135
	v_mfma_f32_32x32x16_bf16 v[34:49], v[204:207], v[100:103], v[34:49]
	v_mfma_f32_32x32x16_bf16 v[66:81], v[200:203], v[104:107], v[66:81]
	v_mfma_f32_32x32x16_bf16 v[50:65], v[190:193], v[104:107], v[50:65]
	v_mfma_f32_32x32x16_bf16 v[34:49], v[186:189], v[104:107], v[34:49]
	ds_read_b128 v[186:189], v185 offset:13920
	ds_read_b128 v[190:193], v185 offset:9312
	ds_read_b128 v[200:203], v185 offset:4704
	ds_read_b128 v[204:207], v185 offset:13888
	ds_read_b128 v[208:211], v185 offset:9280
	ds_read_b128 v[212:215], v185 offset:4672
	ds_read_b128 v[216:219], v185 offset:64
	ds_read_b128 v[220:223], v185 offset:96
	s_waitcnt lgkmcnt(0)
	s_nop 0
	v_mfma_f32_32x32x16_bf16 v[82:97], v[216:219], v[108:111], v[82:97]
	v_mfma_f32_32x32x16_bf16 v[82:97], v[220:223], v[112:115], v[82:97]
	v_mfma_f32_32x32x16_bf16 v[66:81], v[212:215], v[108:111], v[66:81]
	s_nop 10
	v_bfe_i32 v224, v132, 0, 1
	v_bfi_b32 v82, v224, v82, v235
	v_bfe_i32 v224, v132, 1, 1
	v_bfi_b32 v83, v224, v83, v235
	v_mfma_f32_32x32x16_bf16 v[66:81], v[200:203], v[112:115], v[66:81]
	v_bfe_i32 v224, v132, 2, 1
	v_bfi_b32 v84, v224, v84, v235
	v_bfe_i32 v224, v132, 3, 1
	v_bfi_b32 v85, v224, v85, v235
	v_mfma_f32_32x32x16_bf16 v[50:65], v[208:211], v[108:111], v[50:65]
	v_bfe_i32 v224, v132, 8, 1
	v_bfi_b32 v86, v224, v86, v235
	v_bfe_i32 v224, v132, 9, 1
	v_bfi_b32 v87, v224, v87, v235
	v_mfma_f32_32x32x16_bf16 v[50:65], v[190:193], v[112:115], v[50:65]
	v_bfe_i32 v224, v132, 10, 1
	v_bfi_b32 v88, v224, v88, v235
	v_bfe_i32 v224, v132, 11, 1
	v_bfi_b32 v89, v224, v89, v235
	v_mfma_f32_32x32x16_bf16 v[34:49], v[204:207], v[108:111], v[34:49]
	v_bfe_i32 v224, v132, 16, 1
	v_bfi_b32 v90, v224, v90, v235
	v_bfe_i32 v224, v132, 17, 1
	v_bfi_b32 v91, v224, v91, v235
	v_mfma_f32_32x32x16_bf16 v[34:49], v[186:189], v[112:115], v[34:49]
	s_setprio 0
	v_bfe_i32 v224, v132, 18, 1
	v_bfi_b32 v92, v224, v92, v235
	v_bfe_i32 v224, v132, 19, 1
	v_bfi_b32 v93, v224, v93, v235
	v_bfe_i32 v224, v132, 24, 1
	v_bfi_b32 v94, v224, v94, v235
	v_bfe_i32 v224, v132, 25, 1
	v_bfi_b32 v95, v224, v95, v235
	v_bfe_i32 v224, v132, 26, 1
	v_bfi_b32 v96, v224, v96, v235
	v_bfe_i32 v224, v132, 27, 1
	v_bfi_b32 v97, v224, v97, v235
	v_bfe_i32 v224, v133, 0, 1
	v_bfi_b32 v66, v224, v66, v235
	v_bfe_i32 v224, v133, 1, 1
	v_bfi_b32 v67, v224, v67, v235
	v_bfe_i32 v224, v133, 2, 1
	v_bfi_b32 v68, v224, v68, v235
	v_bfe_i32 v224, v133, 3, 1
	v_bfi_b32 v69, v224, v69, v235
	v_bfe_i32 v224, v133, 8, 1
	v_bfi_b32 v70, v224, v70, v235
	v_bfe_i32 v224, v133, 9, 1
	v_bfi_b32 v71, v224, v71, v235
	v_bfe_i32 v224, v133, 10, 1
	v_bfi_b32 v72, v224, v72, v235
	v_bfe_i32 v224, v133, 11, 1
	v_bfi_b32 v73, v224, v73, v235
	v_bfe_i32 v224, v133, 16, 1
	v_bfi_b32 v74, v224, v74, v235
	v_bfe_i32 v224, v133, 17, 1
	v_bfi_b32 v75, v224, v75, v235
	v_bfe_i32 v224, v133, 18, 1
	v_bfi_b32 v76, v224, v76, v235
	v_bfe_i32 v224, v133, 19, 1
	v_bfi_b32 v77, v224, v77, v235
	v_bfe_i32 v224, v133, 24, 1
	v_bfi_b32 v78, v224, v78, v235
	v_bfe_i32 v224, v133, 25, 1
	v_bfi_b32 v79, v224, v79, v235
	v_bfe_i32 v224, v133, 26, 1
	v_bfi_b32 v80, v224, v80, v235
	v_bfe_i32 v224, v133, 27, 1
	v_bfi_b32 v81, v224, v81, v235
	v_bfe_i32 v224, v134, 0, 1
	v_bfi_b32 v50, v224, v50, v235
	v_bfe_i32 v224, v134, 1, 1
	v_bfi_b32 v51, v224, v51, v235
	v_bfe_i32 v224, v134, 2, 1
	v_bfi_b32 v52, v224, v52, v235
	v_bfe_i32 v224, v134, 3, 1
	v_bfi_b32 v53, v224, v53, v235
	v_bfe_i32 v224, v134, 8, 1
	v_bfi_b32 v54, v224, v54, v235
	v_bfe_i32 v224, v134, 9, 1
	v_bfi_b32 v55, v224, v55, v235
	v_bfe_i32 v224, v134, 10, 1
	v_bfi_b32 v56, v224, v56, v235
	v_bfe_i32 v224, v134, 11, 1
	v_bfi_b32 v57, v224, v57, v235
	v_bfe_i32 v224, v134, 16, 1
	v_bfi_b32 v58, v224, v58, v235
	v_bfe_i32 v224, v134, 17, 1
	v_bfi_b32 v59, v224, v59, v235
	v_bfe_i32 v224, v134, 18, 1
	v_bfi_b32 v60, v224, v60, v235
	v_bfe_i32 v224, v134, 19, 1
	v_bfi_b32 v61, v224, v61, v235
; DI float shx(float v, int o, int lane) { return __int_as_float(__builtin_amdgcn_ds_bpermute((lane ^ o) << 2, __float_as_int(v))); }
; DI int crow(int i, int h) { return (i & 3) + 8 * (i >> 2) + 4 * h; }
;     ...
;             if (MODE == 0) {
; #pragma unroll
;                 for (int kb2 = 0; kb2 < NKB; ++kb2) {
;                     const unsigned wsel = ((kb2 & 1) ? (unsigned)(mw[kb2 >> 1] >> 32) : (unsigned)mw[kb2 >> 1]) >> (4 * h);
; #pragma unroll
;                     for (int i = 0; i < 16; ++i) { const int cb = (i & 3) + 8 * (i >> 2); if (!((wsel >> cb) & 1u)) sv[kb2][i] = -1e30f; }
;                 }
;             } else if (key0 + 32 * NKB - 1 > q0) {
;                 const int qq = q0 + r;
; #pragma unroll
;                 for (int kb2 = 0; kb2 < NKB; ++kb2)
; #pragma unroll
;                     for (int i = 0; i < 16; ++i) { if (key0 + 32 * kb2 + crow(i, h) > qq) sv[kb2][i] = -1e30f; }
;             }
;             float mx = -1e30f;
; #pragma unroll
;             for (int kb2 = 0; kb2 < NKB; ++kb2)
; #pragma unroll
;                 for (int i = 0; i < 16; ++i) mx = __builtin_fmaxf(mx, sv[kb2][i]);
;             mx = __builtin_fmaxf(mx, shx(mx, 32, lane));
;             if (__ballot(mx > 8.0f)) {
;                 const float delta = __builtin_fmaxf(mx, 0.f);
;                 const float alpha = __builtin_amdgcn_exp2f(-delta);
;                 nm_run -= delta; l_run *= alpha;
; #pragma unroll
;                 for (int kb2 = 0; kb2 < NKB; ++kb2)
; #pragma unroll
;                     for (int i = 0; i < 16; ++i) sv[kb2][i] -= delta;
; #pragma unroll
;                 for (int db = 0; db < NDB; ++db)
; #pragma unroll
;                     for (int i = 0; i < 16; ++i) ot[db][i] *= alpha;
;             }
	v_bfe_i32 v224, v134, 24, 1
	v_bfi_b32 v62, v224, v62, v235
	v_bfe_i32 v224, v134, 25, 1
	v_bfi_b32 v63, v224, v63, v235
	v_bfe_i32 v224, v134, 26, 1
	v_bfi_b32 v64, v224, v64, v235
	v_bfe_i32 v224, v134, 27, 1
	v_bfi_b32 v65, v224, v65, v235
	v_bfe_i32 v224, v135, 0, 1
	v_bfi_b32 v34, v224, v34, v235
	v_bfe_i32 v224, v135, 1, 1
	v_bfi_b32 v35, v224, v35, v235
	v_bfe_i32 v224, v135, 2, 1
	v_bfi_b32 v36, v224, v36, v235
	v_bfe_i32 v224, v135, 3, 1
	v_bfi_b32 v37, v224, v37, v235
	v_bfe_i32 v224, v135, 8, 1
	v_bfi_b32 v38, v224, v38, v235
	v_bfe_i32 v224, v135, 9, 1
	v_bfi_b32 v39, v224, v39, v235
	v_bfe_i32 v224, v135, 10, 1
	v_bfi_b32 v40, v224, v40, v235
	v_bfe_i32 v224, v135, 11, 1
	v_bfi_b32 v41, v224, v41, v235
	v_bfe_i32 v224, v135, 16, 1
	v_bfi_b32 v42, v224, v42, v235
	v_bfe_i32 v224, v135, 17, 1
	v_bfi_b32 v43, v224, v43, v235
	v_bfe_i32 v224, v135, 18, 1
	v_bfi_b32 v44, v224, v44, v235
	v_bfe_i32 v224, v135, 19, 1
	v_bfi_b32 v45, v224, v45, v235
	v_bfe_i32 v224, v135, 24, 1
	v_bfi_b32 v46, v224, v46, v235
	v_bfe_i32 v224, v135, 25, 1
	v_bfi_b32 v47, v224, v47, v235
	v_bfe_i32 v224, v135, 26, 1
	v_bfi_b32 v48, v224, v48, v235
	v_max3_f32 v33, v82, s61, v83
	v_max3_f32 v33, v33, v84, v85
	v_max3_f32 v33, v33, v86, v87
	v_max3_f32 v33, v33, v88, v89
	v_max3_f32 v33, v33, v90, v91
	v_max3_f32 v33, v33, v92, v93
	v_max3_f32 v33, v33, v94, v95
	v_max3_f32 v33, v33, v96, v97
	v_max3_f32 v33, v33, v66, v67
	v_max3_f32 v33, v33, v68, v69
	v_max3_f32 v33, v33, v70, v71
	v_max3_f32 v33, v33, v72, v73
	v_max3_f32 v33, v33, v74, v75
	v_max3_f32 v33, v33, v76, v77
	v_max3_f32 v33, v33, v78, v79
	v_max3_f32 v33, v33, v80, v81
	v_max3_f32 v33, v33, v50, v51
	v_max3_f32 v33, v33, v52, v53
	v_max3_f32 v33, v33, v54, v55
	v_max3_f32 v33, v33, v56, v57
	v_max3_f32 v33, v33, v58, v59
	v_max3_f32 v33, v33, v60, v61
	v_max3_f32 v33, v33, v62, v63
	v_max3_f32 v33, v33, v64, v65
	v_max3_f32 v33, v33, v34, v35
	v_max3_f32 v33, v33, v36, v37
	v_max3_f32 v33, v33, v38, v39
	v_max3_f32 v33, v33, v40, v41
	v_max3_f32 v33, v33, v42, v43
	v_max3_f32 v33, v33, v44, v45
	v_bfe_i32 v224, v135, 27, 1
	v_bfi_b32 v49, v224, v49, v235
	v_max3_f32 v33, v33, v46, v47
	v_max3_f32 v33, v33, v48, v49
	ds_bpermute_b32 v132, v181, v33
	s_waitcnt lgkmcnt(0)
	v_max_f32_e32 v132, v132, v132
	v_max_f32_e32 v33, v33, v132
	v_cmp_lt_f32_e32 vcc, s33, v33
	s_cbranch_vccz .LBB0_524
	v_max_f32_e32 v33, v33, v33
	v_max_f32_e32 v132, 0, v33
	v_exp_f32_e64 v134, -v132
	v_sub_f32_e32 v32, v32, v132
	v_pk_add_f32 v[82:83], v[82:83], v[132:133] op_sel_hi:[1,0] neg_lo:[0,1] neg_hi:[0,1]
	v_pk_add_f32 v[84:85], v[84:85], v[132:133] op_sel_hi:[1,0] neg_lo:[0,1] neg_hi:[0,1]
	v_pk_add_f32 v[86:87], v[86:87], v[132:133] op_sel_hi:[1,0] neg_lo:[0,1] neg_hi:[0,1]
	v_pk_add_f32 v[88:89], v[88:89], v[132:133] op_sel_hi:[1,0] neg_lo:[0,1] neg_hi:[0,1]
	v_pk_add_f32 v[90:91], v[90:91], v[132:133] op_sel_hi:[1,0] neg_lo:[0,1] neg_hi:[0,1]
	v_pk_add_f32 v[92:93], v[92:93], v[132:133] op_sel_hi:[1,0] neg_lo:[0,1] neg_hi:[0,1]
	v_pk_add_f32 v[94:95], v[94:95], v[132:133] op_sel_hi:[1,0] neg_lo:[0,1] neg_hi:[0,1]
	v_pk_add_f32 v[96:97], v[96:97], v[132:133] op_sel_hi:[1,0] neg_lo:[0,1] neg_hi:[0,1]
	v_pk_add_f32 v[66:67], v[66:67], v[132:133] op_sel_hi:[1,0] neg_lo:[0,1] neg_hi:[0,1]
	v_pk_add_f32 v[68:69], v[68:69], v[132:133] op_sel_hi:[1,0] neg_lo:[0,1] neg_hi:[0,1]
	v_pk_add_f32 v[70:71], v[70:71], v[132:133] op_sel_hi:[1,0] neg_lo:[0,1] neg_hi:[0,1]
	v_pk_add_f32 v[72:73], v[72:73], v[132:133] op_sel_hi:[1,0] neg_lo:[0,1] neg_hi:[0,1]
	v_pk_add_f32 v[74:75], v[74:75], v[132:133] op_sel_hi:[1,0] neg_lo:[0,1] neg_hi:[0,1]
	v_pk_add_f32 v[76:77], v[76:77], v[132:133] op_sel_hi:[1,0] neg_lo:[0,1] neg_hi:[0,1]
	v_pk_add_f32 v[78:79], v[78:79], v[132:133] op_sel_hi:[1,0] neg_lo:[0,1] neg_hi:[0,1]
	v_pk_add_f32 v[80:81], v[80:81], v[132:133] op_sel_hi:[1,0] neg_lo:[0,1] neg_hi:[0,1]
	v_pk_add_f32 v[50:51], v[50:51], v[132:133] op_sel_hi:[1,0] neg_lo:[0,1] neg_hi:[0,1]
	v_pk_add_f32 v[52:53], v[52:53], v[132:133] op_sel_hi:[1,0] neg_lo:[0,1] neg_hi:[0,1]
	v_pk_add_f32 v[54:55], v[54:55], v[132:133] op_sel_hi:[1,0] neg_lo:[0,1] neg_hi:[0,1]
	v_pk_add_f32 v[56:57], v[56:57], v[132:133] op_sel_hi:[1,0] neg_lo:[0,1] neg_hi:[0,1]
	v_pk_add_f32 v[58:59], v[58:59], v[132:133] op_sel_hi:[1,0] neg_lo:[0,1] neg_hi:[0,1]
	v_pk_add_f32 v[60:61], v[60:61], v[132:133] op_sel_hi:[1,0] neg_lo:[0,1] neg_hi:[0,1]
	v_pk_add_f32 v[62:63], v[62:63], v[132:133] op_sel_hi:[1,0] neg_lo:[0,1] neg_hi:[0,1]
	v_pk_add_f32 v[64:65], v[64:65], v[132:133] op_sel_hi:[1,0] neg_lo:[0,1] neg_hi:[0,1]
	v_pk_add_f32 v[34:35], v[34:35], v[132:133] op_sel_hi:[1,0] neg_lo:[0,1] neg_hi:[0,1]
	v_pk_add_f32 v[36:37], v[36:37], v[132:133] op_sel_hi:[1,0] neg_lo:[0,1] neg_hi:[0,1]
	v_pk_add_f32 v[38:39], v[38:39], v[132:133] op_sel_hi:[1,0] neg_lo:[0,1] neg_hi:[0,1]
	v_pk_add_f32 v[40:41], v[40:41], v[132:133] op_sel_hi:[1,0] neg_lo:[0,1] neg_hi:[0,1]
	v_pk_add_f32 v[42:43], v[42:43], v[132:133] op_sel_hi:[1,0] neg_lo:[0,1] neg_hi:[0,1]
	v_pk_add_f32 v[44:45], v[44:45], v[132:133] op_sel_hi:[1,0] neg_lo:[0,1] neg_hi:[0,1]
	v_pk_add_f32 v[46:47], v[46:47], v[132:133] op_sel_hi:[1,0] neg_lo:[0,1] neg_hi:[0,1]
	v_pk_add_f32 v[48:49], v[48:49], v[132:133] op_sel_hi:[1,0] neg_lo:[0,1] neg_hi:[0,1]
	v_pk_mul_f32 v[14:15], v[14:15], v[134:135] op_sel_hi:[1,0]
	v_pk_mul_f32 v[12:13], v[12:13], v[134:135] op_sel_hi:[1,0]
	v_pk_mul_f32 v[10:11], v[10:11], v[134:135] op_sel_hi:[1,0]
	v_pk_mul_f32 v[8:9], v[8:9], v[134:135] op_sel_hi:[1,0]
	v_pk_mul_f32 v[6:7], v[6:7], v[134:135] op_sel_hi:[1,0]
	v_pk_mul_f32 v[4:5], v[4:5], v[134:135] op_sel_hi:[1,0]
	v_pk_mul_f32 v[2:3], v[2:3], v[134:135] op_sel_hi:[1,0]
	v_pk_mul_f32 v[0:1], v[0:1], v[134:135] op_sel_hi:[1,0]
	v_pk_mul_f32 v[30:31], v[30:31], v[134:135] op_sel_hi:[1,0]
	v_pk_mul_f32 v[28:29], v[28:29], v[134:135] op_sel_hi:[1,0]
	v_pk_mul_f32 v[26:27], v[26:27], v[134:135] op_sel_hi:[1,0]
	v_pk_mul_f32 v[24:25], v[24:25], v[134:135] op_sel_hi:[1,0]
	v_pk_mul_f32 v[22:23], v[22:23], v[134:135] op_sel_hi:[1,0]
	v_pk_mul_f32 v[20:21], v[20:21], v[134:135] op_sel_hi:[1,0]
	v_pk_mul_f32 v[18:19], v[18:19], v[134:135] op_sel_hi:[1,0]
	v_pk_mul_f32 v[16:17], v[16:17], v[134:135] op_sel_hi:[1,0]
	v_mul_f32_e32 v184, v184, v134
; #define LAS __attribute__((address_space(3)))
; DI unsigned pk2(float a, float b) { f32x2 v = {a, b}; bf16x2_t r = __builtin_convertvector(v, bf16x2_t); return __builtin_bit_cast(unsigned, r); }
; #define MFMA32(a, b, c) __builtin_amdgcn_mfma_f32_32x32x16_bf16((a), (b), (c), 0, 0, 0)
;     ...
;             float ps = 0.f;
; #pragma unroll
;             for (int kb2 = 0; kb2 < NKB; ++kb2)
; #pragma unroll
;                 for (int i = 0; i < 16; ++i) { sv[kb2][i] = __builtin_amdgcn_exp2f(sv[kb2][i]); ps += sv[kb2][i]; }
;             l_run += ps;
;             const LAS unsigned char* vb_ = lds + st * STAGE + KBYTES + sub * 32 * NKB * 2;
; #pragma unroll
;             for (int kb2 = 0; kb2 < NKB; ++kb2)
; #pragma unroll
;                 for (int s = 0; s < 2; ++s) {
;                     u32x2 vlo[NDB], vhi[NDB];
; #pragma unroll
;                     for (int db = 0; db < NDB; ++db) { const LAS unsigned char* vp = vb_ + (32 * db + r) * VP + (32 * kb2 + 16 * s + 4 * h) * 2;
;                         vlo[db] = *(const LAS u32x2*)vp; vhi[db] = *(const LAS u32x2*)(vp + 16); }
;                     u32x4 pw;
;                     pw.x = pk2(sv[kb2][8 * s + 0], sv[kb2][8 * s + 1]); pw.y = pk2(sv[kb2][8 * s + 2], sv[kb2][8 * s + 3]); pw.z = pk2(sv[kb2][8 * s + 4], sv[kb2][8 * s + 5]); pw.w = pk2(sv[kb2][8 * s + 6], sv[kb2][8 * s + 7]);
;                     const bf16x8 pf = __builtin_bit_cast(bf16x8, pw);
;                     if (NDB == 2) asm volatile("" : "+v"(vlo[0]), "+v"(vhi[0]), "+v"(vlo[1]), "+v"(vhi[1]));
;                     else asm volatile("" : "+v"(vlo[0]), "+v"(vhi[0]), "+v"(vlo[1]), "+v"(vhi[1]), "+v"(vlo[NDB - 2]), "+v"(vhi[NDB - 2]), "+v"(vlo[NDB - 1]), "+v"(vhi[NDB - 1]));
; #pragma unroll
;                     for (int db = 0; db < NDB; ++db) { const u32x4 vw = {vlo[db].x, vlo[db].y, vhi[db].x, vhi[db].y};
;                         ot[db] = MFMA32(__builtin_bit_cast(bf16x8, vw), pf, ot[db]); }
;                 }
;         }
;         }
;         if (more && PV != 1) ATT_STORE(st ^ 1);
.LBB0_524:
	v_add3_u32 v132, s9, v136, v183
	v_exp_f32_e32 v33, v82
	v_exp_f32_e32 v82, v83
	v_exp_f32_e32 v83, v84
	v_exp_f32_e32 v84, v85
	v_exp_f32_e32 v85, v86
	v_exp_f32_e32 v86, v87
	v_exp_f32_e32 v87, v88
	v_exp_f32_e32 v88, v89
	v_exp_f32_e32 v89, v90
	v_exp_f32_e32 v90, v91
	v_exp_f32_e32 v91, v92
	v_exp_f32_e32 v92, v93
	v_exp_f32_e32 v93, v94
	v_exp_f32_e32 v94, v95
	v_exp_f32_e32 v95, v96
	v_exp_f32_e32 v96, v97
	v_add_u32_e32 v97, 0x4800, v132
	v_add_u32_e32 v132, 0x6800, v132
	ds_read2_b64 v[190:193], v132 offset0:32 offset1:34
	ds_read2_b64 v[186:189], v97 offset1:2
	v_cvt_pk_bf16_f32 v200, v33, v82
	v_cvt_pk_bf16_f32 v201, v83, v84
	v_cvt_pk_bf16_f32 v202, v85, v86
	s_waitcnt lgkmcnt(1)
	v_mov_b64_e32 v[134:135], v[192:193]
	s_waitcnt lgkmcnt(0)
	v_cvt_pk_bf16_f32 v203, v87, v88
	v_mov_b32_e32 v192, v134
	v_mov_b32_e32 v193, v135
	s_setprio 1
	v_mfma_f32_32x32x16_bf16 v[0:15], v[186:189], v[200:203], v[0:15]
	v_exp_f32_e32 v66, v66
	v_exp_f32_e32 v67, v67
	v_exp_f32_e32 v68, v68
	v_exp_f32_e32 v69, v69
	v_exp_f32_e32 v70, v70
	v_exp_f32_e32 v71, v71
	v_exp_f32_e32 v72, v72
	v_mfma_f32_32x32x16_bf16 v[16:31], v[190:193], v[200:203], v[16:31]
	ds_read2_b64 v[186:189], v97 offset0:4 offset1:6
	ds_read2_b64 v[190:193], v132 offset0:36 offset1:38
	v_cvt_pk_bf16_f32 v200, v89, v90
	v_cvt_pk_bf16_f32 v201, v91, v92
	v_cvt_pk_bf16_f32 v202, v93, v94
	v_cvt_pk_bf16_f32 v203, v95, v96
	s_waitcnt lgkmcnt(0)
	v_exp_f32_e32 v73, v73
	v_exp_f32_e32 v74, v74
	v_mfma_f32_32x32x16_bf16 v[0:15], v[186:189], v[200:203], v[0:15]
	v_exp_f32_e32 v75, v75
	v_exp_f32_e32 v76, v76
	v_exp_f32_e32 v77, v77
	v_exp_f32_e32 v78, v78
	v_exp_f32_e32 v79, v79
	v_exp_f32_e32 v80, v80
	v_exp_f32_e32 v81, v81
	v_mfma_f32_32x32x16_bf16 v[16:31], v[190:193], v[200:203], v[16:31]
	ds_read2_b64 v[186:189], v97 offset0:8 offset1:10
	ds_read2_b64 v[190:193], v132 offset0:40 offset1:42
	v_cvt_pk_bf16_f32 v200, v66, v67
	v_cvt_pk_bf16_f32 v201, v68, v69
	v_cvt_pk_bf16_f32 v202, v70, v71
	s_waitcnt lgkmcnt(1)
	v_mov_b64_e32 v[134:135], v[188:189]
	s_waitcnt lgkmcnt(0)
	v_cvt_pk_bf16_f32 v203, v72, v73
	v_mov_b32_e32 v188, v134
	v_mov_b32_e32 v189, v135
	v_mfma_f32_32x32x16_bf16 v[16:31], v[190:193], v[200:203], v[16:31]
	v_exp_f32_e32 v50, v50
	v_exp_f32_e32 v51, v51
	v_exp_f32_e32 v52, v52
	v_exp_f32_e32 v53, v53
	v_exp_f32_e32 v54, v54
	v_exp_f32_e32 v55, v55
	v_exp_f32_e32 v56, v56
	v_mfma_f32_32x32x16_bf16 v[0:15], v[186:189], v[200:203], v[0:15]
	ds_read2_b64 v[186:189], v97 offset0:12 offset1:14
	ds_read2_b64 v[190:193], v132 offset0:44 offset1:46
	v_cvt_pk_bf16_f32 v200, v74, v75
	v_cvt_pk_bf16_f32 v201, v76, v77
	v_cvt_pk_bf16_f32 v202, v78, v79
	v_cvt_pk_bf16_f32 v203, v80, v81
	s_waitcnt lgkmcnt(0)
	v_exp_f32_e32 v57, v57
	v_exp_f32_e32 v58, v58
	v_mfma_f32_32x32x16_bf16 v[0:15], v[186:189], v[200:203], v[0:15]
	v_exp_f32_e32 v59, v59
	v_exp_f32_e32 v60, v60
	v_exp_f32_e32 v61, v61
	v_exp_f32_e32 v62, v62
	v_exp_f32_e32 v63, v63
	v_exp_f32_e32 v64, v64
	v_exp_f32_e32 v65, v65
	v_mfma_f32_32x32x16_bf16 v[16:31], v[190:193], v[200:203], v[16:31]
	ds_read2_b64 v[186:189], v97 offset0:16 offset1:18
	ds_read2_b64 v[190:193], v132 offset0:48 offset1:50
	v_cvt_pk_bf16_f32 v200, v50, v51
	v_cvt_pk_bf16_f32 v201, v52, v53
	v_cvt_pk_bf16_f32 v202, v54, v55
	s_waitcnt lgkmcnt(1)
	v_mov_b64_e32 v[134:135], v[188:189]
	s_waitcnt lgkmcnt(0)
	v_cvt_pk_bf16_f32 v203, v56, v57
	v_mov_b32_e32 v188, v134
	v_mov_b32_e32 v189, v135
	v_mfma_f32_32x32x16_bf16 v[16:31], v[190:193], v[200:203], v[16:31]
	v_exp_f32_e32 v34, v34
	v_exp_f32_e32 v35, v35
	v_exp_f32_e32 v36, v36
	v_exp_f32_e32 v37, v37
	v_exp_f32_e32 v38, v38
	v_exp_f32_e32 v39, v39
	v_exp_f32_e32 v40, v40
	v_mfma_f32_32x32x16_bf16 v[0:15], v[186:189], v[200:203], v[0:15]
	ds_read2_b64 v[186:189], v97 offset0:20 offset1:22
	ds_read2_b64 v[190:193], v132 offset0:52 offset1:54
	v_cvt_pk_bf16_f32 v200, v58, v59
	v_cvt_pk_bf16_f32 v201, v60, v61
	v_cvt_pk_bf16_f32 v202, v62, v63
	v_cvt_pk_bf16_f32 v203, v64, v65
	s_waitcnt lgkmcnt(0)
	v_mov_b64_e32 v[134:135], v[192:193]
	v_exp_f32_e32 v41, v41
	v_mov_b32_e32 v192, v134
	v_mov_b32_e32 v193, v135
	v_mfma_f32_32x32x16_bf16 v[0:15], v[186:189], v[200:203], v[0:15]
	v_exp_f32_e32 v42, v42
	v_exp_f32_e32 v43, v43
	v_exp_f32_e32 v44, v44
	v_exp_f32_e32 v45, v45
	v_exp_f32_e32 v46, v46
	v_exp_f32_e32 v47, v47
	v_exp_f32_e32 v48, v48
	v_mfma_f32_32x32x16_bf16 v[16:31], v[190:193], v[200:203], v[16:31]
	ds_read2_b64 v[186:189], v97 offset0:24 offset1:26
	ds_read2_b64 v[190:193], v132 offset0:56 offset1:58
	v_cvt_pk_bf16_f32 v200, v34, v35
	v_cvt_pk_bf16_f32 v201, v36, v37
	v_cvt_pk_bf16_f32 v202, v38, v39
	v_cvt_pk_bf16_f32 v203, v40, v41
	s_waitcnt lgkmcnt(0)
	v_exp_f32_e32 v49, v49
	s_and_b64 vcc, exec, s[4:5]
	v_mfma_f32_32x32x16_bf16 v[0:15], v[186:189], v[200:203], v[0:15]
	ds_read2_b64 v[186:189], v97 offset0:28 offset1:30
	ds_read2_b64 v[132:135], v132 offset0:60 offset1:62
	s_waitcnt lgkmcnt(0)
	v_mfma_f32_32x32x16_bf16 v[16:31], v[190:193], v[200:203], v[16:31]
	v_cvt_pk_bf16_f32 v190, v42, v43
	v_cvt_pk_bf16_f32 v191, v44, v45
	v_cvt_pk_bf16_f32 v192, v46, v47
	v_cvt_pk_bf16_f32 v193, v48, v49
	s_nop 1
	v_mfma_f32_32x32x16_bf16 v[0:15], v[186:189], v[190:193], v[0:15]
	v_mfma_f32_32x32x16_bf16 v[16:31], v[132:135], v[190:193], v[16:31]
	s_setprio 0
	s_cbranch_vccz .LBB0_519
	s_xor_b32 s4, s7, 1
	s_mul_i32 s4, s4, 0x8a00
	s_add_i32 s4, s4, 0
	v_add_u32_e32 v97, s4, v176
	ds_write_b128 v97, v[116:119]
	v_add_u32_e32 v97, s4, v177
	ds_write_b128 v97, v[120:123]
	v_add_u32_e32 v97, s4, v178
	v_add_u32_e32 v97, 0x4800, v97
	ds_write2_b64 v97, v[124:125], v[126:127] offset1:1
	v_add_u32_e32 v97, s4, v179
	v_add_u32_e32 v97, 0x4800, v97
	ds_write2_b64 v97, v[128:129], v[130:131] offset1:1
	s_branch .LBB0_519
